# plus residual-add epilogues of phases 2, 7, 10: all 16 residual loads issued in one burst before the drain wait
# baseline (speedup 1.0000x reference)
; __device__ __forceinline__ unsigned cvt_pk_bf16(float lo, float hi) { cvf32x2_t v = {lo, hi}; cvbf16x2_t b = __builtin_convertvector(v, cvbf16x2_t); return __builtin_bit_cast(unsigned, b); }
; #define PG8_WAIT_V(n) asm volatile("s_waitcnt vmcnt(" #n ")" ::: "memory")
; #define PG8_BAR __builtin_amdgcn_s_barrier()
; __device__ __forceinline__ float bfl(unsigned w) { return __uint_as_float(w << 16); }
; __device__ __forceinline__ float bfh(unsigned w) { return __uint_as_float(w & 0xffff0000u); }
; template <class Epi, class Sched, bool ALIGN_EPI = false, bool SP2 = false>
; __device__ __forceinline__ void gemm_phase(PG8_LAS unsigned char* lds, const Gemm g, const Sched& S, const Epi& E) {
;     ...
;     PG8_WAIT_V(0);
;     if constexpr (!ALIGN_EPI) { if (wr == 0) PG8_BAR; }
;     PG8_BAR;
;     if constexpr (Epi::AFTER_DRAIN) { E.fused(acc, cur, wr, wc, fr, fq, lds, wid, lane); S.done(cur); }
;     __device__ __forceinline__ void fused(f32x4 (&acc)[2][2][4][2], const Unit& u, int wr, int wc, int fr, int fq, PG8_LAS unsigned char* lds, int wid, int lane) const {
;     ...
;             for (int m = 0; m < 4; ++m) { const int row = row0 + ai * HALF + m * 16; const size_t off = (size_t)row * 1024 + col0; float ss = 0.f;
; #pragma unroll
;                 for (int bj = 0; bj < 2; ++bj) { const size_t o = off + bj * HALF; f32x4 x0, x1;
;                     if (xin32) { x0 = *(const f32x4*)(xin32 + o); x1 = *(const f32x4*)(xin32 + o + 4); }
;                     else { const u32x4 w = *(const u32x4*)(xb + o); x0 = (f32x4){bfl(w.x), bfh(w.x), bfl(w.y), bfh(w.y)}; x1 = (f32x4){bfl(w.z), bfh(w.z), bfl(w.w), bfh(w.w)}; }
;                     const f32x4 v0 = x0 + acc[ai][bj][m][0] * scale, v1 = x1 + acc[ai][bj][m][1] * scale;
;                     ss += ((v0[0] * v0[0] + v0[1] * v0[1]) + (v0[2] * v0[2] + v0[3] * v0[3])) + ((v1[0] * v1[0] + v1[1] * v1[1]) + (v1[2] * v1[2] + v1[3] * v1[3]));
;                     u32x4 w; w.x = cvt_pk_bf16(v0[0], v0[1]); w.y = cvt_pk_bf16(v0[2], v0[3]); w.z = cvt_pk_bf16(v1[0], v1[1]); w.w = cvt_pk_bf16(v1[2], v1[3]); st_wt16(xb + o, w); }
;                 ss += __shfl_xor(ss, 16); ss += __shfl_xor(ss, 32);
;                 if (fq == 0) P[(ai * HALF + wr * 64 + m * 16 + fr) * 4 + wc] = ss; }
.LBB0_371:
	s_lshl_b32 s6, s31, 8
	s_add_i32 s5, s6, s38
	s_lshl_b32 s4, s30, 5
	v_or_b32_e32 v128, s5, v150
	s_lshl_b32 s5, s41, 8
	s_or_b32 s4, s5, s4
	v_and_or_b32 v130, v149, 24, s4
	v_ashrrev_i32_e32 v129, 31, v128
	v_ashrrev_i32_e32 v131, 31, v130
	v_lshlrev_b64 v[132:133], 10, v[128:129]
	v_lshl_add_u64 v[132:133], v[132:133], 0, v[130:131]
	v_lshl_add_u64 v[142:143], v[132:133], 1, s[54:55]
	s_mov_b64 s[96:97], 0x8000
	v_lshl_add_u64 v[154:155], v[142:143], 0, s[96:97]
	s_mov_b64 s[96:97], 0x10000
	v_lshl_add_u64 v[210:211], v[142:143], 0, s[96:97]
	s_mov_b64 s[96:97], 0x18000
	v_lshl_add_u64 v[224:225], v[142:143], 0, s[96:97]
	s_mov_b64 s[96:97], 0x40000
	v_lshl_add_u64 v[226:227], v[142:143], 0, s[96:97]
	s_mov_b64 s[96:97], 0x48000
	v_lshl_add_u64 v[228:229], v[142:143], 0, s[96:97]
	s_mov_b64 s[96:97], 0x50000
	v_lshl_add_u64 v[230:231], v[142:143], 0, s[96:97]
	s_mov_b64 s[96:97], 0x58000
	v_lshl_add_u64 v[232:233], v[142:143], 0, s[96:97]
	global_load_dwordx4 v[156:159], v[142:143], off
	global_load_dwordx4 v[160:163], v[142:143], off offset:256
	global_load_dwordx4 v[164:167], v[154:155], off
	global_load_dwordx4 v[168:171], v[154:155], off offset:256
	global_load_dwordx4 v[172:175], v[210:211], off
	global_load_dwordx4 v[176:179], v[210:211], off offset:256
	global_load_dwordx4 v[180:183], v[224:225], off
	global_load_dwordx4 v[184:187], v[224:225], off offset:256
	global_load_dwordx4 v[188:191], v[226:227], off
	global_load_dwordx4 v[192:195], v[226:227], off offset:256
	global_load_dwordx4 v[196:199], v[228:229], off
	global_load_dwordx4 v[200:203], v[228:229], off offset:256
	global_load_dwordx4 v[204:207], v[230:231], off
	global_load_dwordx4 v[212:215], v[230:231], off offset:256
	global_load_dwordx4 v[216:219], v[232:233], off
	global_load_dwordx4 v[220:223], v[232:233], off offset:256
	s_waitcnt vmcnt(0)
	s_cmpk_gt_u32 s25, 0xff
	s_cbranch_scc1 .LBB0_373
	s_barrier
.LBB0_373:
	s_barrier
	v_mbcnt_lo_u32_b32 v132, -1, 0
	v_mbcnt_hi_u32_b32 v132, -1, v132
	v_and_b32_e32 v144, 64, v132
	v_xor_b32_e32 v133, 16, v132
	v_add_u32_e32 v144, 64, v144
	v_xor_b32_e32 v145, 32, v132
	v_cmp_lt_i32_e32 vcc, v133, v144
	s_lshl_b32 s7, s30, 2
	s_add_i32 s7, s7, 0
	v_cndmask_b32_e32 v133, v132, v133, vcc
	v_cmp_lt_i32_e32 vcc, v145, v144
	v_lshlrev_b32_e32 v133, 2, v133
	v_cmp_gt_u32_e64 s[4:5], 16, v208
	v_cndmask_b32_e32 v132, v132, v145, vcc
	v_lshlrev_b32_e32 v132, 2, v132
	v_lshlrev_b32_e32 v144, 16, v156
	v_and_b32_e32 v145, 0xffff0000, v156
	v_lshlrev_b32_e32 v134, 16, v157
	v_and_b32_e32 v135, 0xffff0000, v157
	v_lshlrev_b32_e32 v146, 16, v158
	v_and_b32_e32 v147, 0xffff0000, v158
	v_lshlrev_b32_e32 v136, 16, v159
	v_and_b32_e32 v137, 0xffff0000, v159
	v_lshlrev_b32_e32 v150, 16, v160
	v_and_b32_e32 v151, 0xffff0000, v160
	v_lshlrev_b32_e32 v138, 16, v161
	v_and_b32_e32 v139, 0xffff0000, v161
	v_lshlrev_b32_e32 v152, 16, v162
	v_and_b32_e32 v153, 0xffff0000, v162
	v_lshlrev_b32_e32 v140, 16, v163
	v_and_b32_e32 v141, 0xffff0000, v163
	v_pk_fma_f32 v[126:127], v[126:127], 0.5, v[134:135] op_sel_hi:[1,0,1]
	v_pk_fma_f32 v[124:125], v[124:125], 0.5, v[144:145] op_sel_hi:[1,0,1]
	v_pk_fma_f32 v[122:123], v[122:123], 0.5, v[136:137] op_sel_hi:[1,0,1]
	v_pk_fma_f32 v[120:121], v[120:121], 0.5, v[146:147] op_sel_hi:[1,0,1]
	v_pk_fma_f32 v[118:119], v[118:119], 0.5, v[138:139] op_sel_hi:[1,0,1]
	v_pk_fma_f32 v[116:117], v[116:117], 0.5, v[150:151] op_sel_hi:[1,0,1]
	v_pk_fma_f32 v[134:135], v[114:115], 0.5, v[140:141] op_sel_hi:[1,0,1]
	v_pk_fma_f32 v[136:137], v[112:113], 0.5, v[152:153] op_sel_hi:[1,0,1]
	v_mul_f32_e32 v115, v125, v125
	v_mul_f32_e32 v138, v127, v127
	v_mul_f32_e32 v139, v121, v121
	v_mul_f32_e32 v140, v123, v123
	v_cvt_pk_bf16_f32 v112, v124, v125
	v_cvt_pk_bf16_f32 v113, v126, v127
	v_cvt_pk_bf16_f32 v114, v120, v121
	v_mul_f32_e32 v121, v117, v117
	v_mul_f32_e32 v125, v119, v119
	v_mul_f32_e32 v127, v137, v137
	v_mul_f32_e32 v141, v135, v135
	v_fmac_f32_e32 v115, v124, v124
	v_fmac_f32_e32 v138, v126, v126
	v_fmac_f32_e32 v139, v120, v120
	v_fmac_f32_e32 v140, v122, v122
	v_fmac_f32_e32 v121, v116, v116
	v_fmac_f32_e32 v125, v118, v118
	v_fmac_f32_e32 v127, v136, v136
	v_fmac_f32_e32 v141, v134, v134
	v_add_f32_e32 v115, v115, v138
	v_add_f32_e32 v120, v139, v140
	v_add_f32_e32 v121, v121, v125
	v_add_f32_e32 v124, v127, v141
	v_add_f32_e32 v115, v115, v120
	v_add_f32_e32 v120, v121, v124
	v_add_f32_e32 v120, v115, v120
	ds_bpermute_b32 v121, v133, v120
	v_cvt_pk_bf16_f32 v115, v122, v123
	global_store_dwordx4 v[142:143], v[112:115], off
	v_cvt_pk_bf16_f32 v116, v116, v117
	v_cvt_pk_bf16_f32 v117, v118, v119
	s_waitcnt lgkmcnt(0)
	v_add_f32_e32 v113, v120, v121
	ds_bpermute_b32 v114, v132, v113
	v_cvt_pk_bf16_f32 v118, v136, v137
	v_cvt_pk_bf16_f32 v119, v134, v135
	v_lshl_add_u32 v112, v148, 4, s7
	global_store_dwordx4 v[142:143], v[116:119], off offset:256
	s_and_saveexec_b64 s[8:9], s[4:5]
	s_cbranch_execz .LBB0_375
	s_waitcnt lgkmcnt(0)
	v_add_f32_e32 v113, v113, v114
	ds_write_b32 v112, v113
; __device__ __forceinline__ unsigned cvt_pk_bf16(float lo, float hi) { cvf32x2_t v = {lo, hi}; cvbf16x2_t b = __builtin_convertvector(v, cvbf16x2_t); return __builtin_bit_cast(unsigned, b); }
; __device__ __forceinline__ float bfl(unsigned w) { return __uint_as_float(w << 16); }
; __device__ __forceinline__ float bfh(unsigned w) { return __uint_as_float(w & 0xffff0000u); }
;     __device__ __forceinline__ void fused(f32x4 (&acc)[2][2][4][2], const Unit& u, int wr, int wc, int fr, int fq, PG8_LAS unsigned char* lds, int wid, int lane) const {
;     ...
;             for (int m = 0; m < 4; ++m) { const int row = row0 + ai * HALF + m * 16; const size_t off = (size_t)row * 1024 + col0; float ss = 0.f;
; #pragma unroll
;                 for (int bj = 0; bj < 2; ++bj) { const size_t o = off + bj * HALF; f32x4 x0, x1;
;                     if (xin32) { x0 = *(const f32x4*)(xin32 + o); x1 = *(const f32x4*)(xin32 + o + 4); }
;                     else { const u32x4 w = *(const u32x4*)(xb + o); x0 = (f32x4){bfl(w.x), bfh(w.x), bfl(w.y), bfh(w.y)}; x1 = (f32x4){bfl(w.z), bfh(w.z), bfl(w.w), bfh(w.w)}; }
;                     const f32x4 v0 = x0 + acc[ai][bj][m][0] * scale, v1 = x1 + acc[ai][bj][m][1] * scale;
;                     ss += ((v0[0] * v0[0] + v0[1] * v0[1]) + (v0[2] * v0[2] + v0[3] * v0[3])) + ((v1[0] * v1[0] + v1[1] * v1[1]) + (v1[2] * v1[2] + v1[3] * v1[3]));
;                     u32x4 w; w.x = cvt_pk_bf16(v0[0], v0[1]); w.y = cvt_pk_bf16(v0[2], v0[3]); w.z = cvt_pk_bf16(v1[0], v1[1]); w.w = cvt_pk_bf16(v1[2], v1[3]); st_wt16(xb + o, w); }
;                 ss += __shfl_xor(ss, 16); ss += __shfl_xor(ss, 32);
;                 if (fq == 0) P[(ai * HALF + wr * 64 + m * 16 + fr) * 4 + wc] = ss; }
.LBB0_375:
	s_or_b64 exec, exec, s[8:9]
	s_waitcnt lgkmcnt(0)
	v_or_b32_e32 v114, 16, v128
	v_ashrrev_i32_e32 v115, 31, v114
	v_lshlrev_b64 v[114:115], 10, v[114:115]
	v_lshl_add_u64 v[114:115], v[114:115], 0, v[130:131]
	v_lshl_add_u64 v[122:123], v[114:115], 1, s[54:55]
	v_lshlrev_b32_e32 v124, 16, v164
	v_and_b32_e32 v125, 0xffff0000, v164
	v_lshlrev_b32_e32 v114, 16, v165
	v_and_b32_e32 v115, 0xffff0000, v165
	v_lshlrev_b32_e32 v126, 16, v166
	v_and_b32_e32 v127, 0xffff0000, v166
	v_lshlrev_b32_e32 v116, 16, v167
	v_and_b32_e32 v117, 0xffff0000, v167
	v_lshlrev_b32_e32 v134, 16, v168
	v_and_b32_e32 v135, 0xffff0000, v168
	v_lshlrev_b32_e32 v118, 16, v169
	v_and_b32_e32 v119, 0xffff0000, v169
	v_lshlrev_b32_e32 v136, 16, v170
	v_and_b32_e32 v137, 0xffff0000, v170
	v_lshlrev_b32_e32 v120, 16, v171
	v_and_b32_e32 v121, 0xffff0000, v171
	v_pk_fma_f32 v[110:111], v[110:111], 0.5, v[114:115] op_sel_hi:[1,0,1]
	v_pk_fma_f32 v[108:109], v[108:109], 0.5, v[124:125] op_sel_hi:[1,0,1]
	v_pk_fma_f32 v[106:107], v[106:107], 0.5, v[116:117] op_sel_hi:[1,0,1]
	v_pk_fma_f32 v[104:105], v[104:105], 0.5, v[126:127] op_sel_hi:[1,0,1]
	v_pk_fma_f32 v[102:103], v[102:103], 0.5, v[118:119] op_sel_hi:[1,0,1]
	v_pk_fma_f32 v[100:101], v[100:101], 0.5, v[134:135] op_sel_hi:[1,0,1]
	v_pk_fma_f32 v[114:115], v[98:99], 0.5, v[120:121] op_sel_hi:[1,0,1]
	v_pk_fma_f32 v[116:117], v[96:97], 0.5, v[136:137] op_sel_hi:[1,0,1]
	v_mul_f32_e32 v98, v109, v109
	v_mul_f32_e32 v99, v111, v111
	v_mul_f32_e32 v113, v105, v105
	v_mul_f32_e32 v118, v107, v107
	v_cvt_pk_bf16_f32 v96, v108, v109
	v_cvt_pk_bf16_f32 v97, v110, v111
	v_mul_f32_e32 v109, v101, v101
	v_mul_f32_e32 v111, v103, v103
	v_mul_f32_e32 v119, v117, v117
	v_mul_f32_e32 v120, v115, v115
	v_fmac_f32_e32 v98, v108, v108
	v_fmac_f32_e32 v99, v110, v110
	v_fmac_f32_e32 v113, v104, v104
	v_fmac_f32_e32 v118, v106, v106
	v_fmac_f32_e32 v109, v100, v100
	v_fmac_f32_e32 v111, v102, v102
	v_fmac_f32_e32 v119, v116, v116
	v_fmac_f32_e32 v120, v114, v114
	v_add_f32_e32 v98, v98, v99
	v_add_f32_e32 v99, v113, v118
	v_add_f32_e32 v108, v109, v111
	v_add_f32_e32 v109, v119, v120
	v_add_f32_e32 v98, v98, v99
	v_add_f32_e32 v99, v108, v109
	v_add_f32_e32 v108, v98, v99
	ds_bpermute_b32 v109, v133, v108
	v_cvt_pk_bf16_f32 v98, v104, v105
	v_cvt_pk_bf16_f32 v99, v106, v107
	global_store_dwordx4 v[122:123], v[96:99], off
	s_waitcnt lgkmcnt(0)
	s_nop 0
	v_add_f32_e32 v96, v108, v109
	ds_bpermute_b32 v97, v132, v96
	v_cvt_pk_bf16_f32 v98, v100, v101
	v_cvt_pk_bf16_f32 v99, v102, v103
	v_cvt_pk_bf16_f32 v100, v116, v117
	v_cvt_pk_bf16_f32 v101, v114, v115
	global_store_dwordx4 v[122:123], v[98:101], off offset:256
	s_and_saveexec_b64 s[8:9], s[4:5]
	s_cbranch_execz .LBB0_377
	s_waitcnt lgkmcnt(0)
	v_add_f32_e32 v96, v96, v97
	ds_write_b32 v112, v96 offset:256
.LBB0_377:
	s_or_b64 exec, exec, s[8:9]
	v_or_b32_e32 v96, 32, v128
	s_waitcnt lgkmcnt(0)
	v_ashrrev_i32_e32 v97, 31, v96
	v_lshlrev_b64 v[96:97], 10, v[96:97]
	v_lshl_add_u64 v[96:97], v[96:97], 0, v[130:131]
	v_lshl_add_u64 v[104:105], v[96:97], 1, s[54:55]
	v_lshlrev_b32_e32 v106, 16, v172
	v_and_b32_e32 v107, 0xffff0000, v172
	v_lshlrev_b32_e32 v96, 16, v173
	v_and_b32_e32 v97, 0xffff0000, v173
	v_lshlrev_b32_e32 v108, 16, v174
	v_and_b32_e32 v109, 0xffff0000, v174
	v_lshlrev_b32_e32 v98, 16, v175
	v_and_b32_e32 v99, 0xffff0000, v175
	v_lshlrev_b32_e32 v110, 16, v176
	v_and_b32_e32 v111, 0xffff0000, v176
	v_lshlrev_b32_e32 v100, 16, v177
	v_and_b32_e32 v101, 0xffff0000, v177
	v_lshlrev_b32_e32 v114, 16, v178
	v_and_b32_e32 v115, 0xffff0000, v178
	v_lshlrev_b32_e32 v102, 16, v179
	v_and_b32_e32 v103, 0xffff0000, v179
	v_pk_fma_f32 v[94:95], v[94:95], 0.5, v[96:97] op_sel_hi:[1,0,1]
	v_pk_fma_f32 v[92:93], v[92:93], 0.5, v[106:107] op_sel_hi:[1,0,1]
	v_pk_fma_f32 v[90:91], v[90:91], 0.5, v[98:99] op_sel_hi:[1,0,1]
	v_pk_fma_f32 v[88:89], v[88:89], 0.5, v[108:109] op_sel_hi:[1,0,1]
	v_pk_fma_f32 v[86:87], v[86:87], 0.5, v[100:101] op_sel_hi:[1,0,1]
	v_pk_fma_f32 v[84:85], v[84:85], 0.5, v[110:111] op_sel_hi:[1,0,1]
	v_pk_fma_f32 v[96:97], v[82:83], 0.5, v[102:103] op_sel_hi:[1,0,1]
	v_pk_fma_f32 v[98:99], v[80:81], 0.5, v[114:115] op_sel_hi:[1,0,1]
	v_mul_f32_e32 v82, v93, v93
	v_mul_f32_e32 v83, v95, v95
	v_mul_f32_e32 v100, v89, v89
	v_mul_f32_e32 v101, v91, v91
	v_cvt_pk_bf16_f32 v80, v92, v93
	v_cvt_pk_bf16_f32 v81, v94, v95
	v_mul_f32_e32 v93, v85, v85
	v_mul_f32_e32 v95, v87, v87
	v_mul_f32_e32 v102, v99, v99
	v_mul_f32_e32 v103, v97, v97
	v_fmac_f32_e32 v82, v92, v92
	v_fmac_f32_e32 v83, v94, v94
	v_fmac_f32_e32 v100, v88, v88
	v_fmac_f32_e32 v101, v90, v90
	v_fmac_f32_e32 v93, v84, v84
	v_fmac_f32_e32 v95, v86, v86
	v_fmac_f32_e32 v102, v98, v98
	v_fmac_f32_e32 v103, v96, v96
	v_add_f32_e32 v82, v82, v83
	v_add_f32_e32 v83, v100, v101
	v_add_f32_e32 v92, v93, v95
	v_add_f32_e32 v93, v102, v103
	v_add_f32_e32 v82, v82, v83
	v_add_f32_e32 v83, v92, v93
	v_add_f32_e32 v92, v82, v83
	ds_bpermute_b32 v93, v133, v92
	v_cvt_pk_bf16_f32 v82, v88, v89
	v_cvt_pk_bf16_f32 v83, v90, v91
	global_store_dwordx4 v[104:105], v[80:83], off
	s_waitcnt lgkmcnt(0)
	s_nop 0
	v_add_f32_e32 v80, v92, v93
	ds_bpermute_b32 v81, v132, v80
	v_cvt_pk_bf16_f32 v82, v84, v85
	v_cvt_pk_bf16_f32 v83, v86, v87
	v_cvt_pk_bf16_f32 v84, v98, v99
	v_cvt_pk_bf16_f32 v85, v96, v97
	global_store_dwordx4 v[104:105], v[82:85], off offset:256
	s_and_saveexec_b64 s[8:9], s[4:5]
	s_cbranch_execz .LBB0_379
	s_waitcnt lgkmcnt(0)
	v_add_f32_e32 v80, v80, v81
	ds_write_b32 v112, v80 offset:512
; __device__ __forceinline__ unsigned cvt_pk_bf16(float lo, float hi) { cvf32x2_t v = {lo, hi}; cvbf16x2_t b = __builtin_convertvector(v, cvbf16x2_t); return __builtin_bit_cast(unsigned, b); }
; __device__ __forceinline__ float bfl(unsigned w) { return __uint_as_float(w << 16); }
; __device__ __forceinline__ float bfh(unsigned w) { return __uint_as_float(w & 0xffff0000u); }
;     __device__ __forceinline__ void fused(f32x4 (&acc)[2][2][4][2], const Unit& u, int wr, int wc, int fr, int fq, PG8_LAS unsigned char* lds, int wid, int lane) const {
;     ...
;             for (int m = 0; m < 4; ++m) { const int row = row0 + ai * HALF + m * 16; const size_t off = (size_t)row * 1024 + col0; float ss = 0.f;
; #pragma unroll
;                 for (int bj = 0; bj < 2; ++bj) { const size_t o = off + bj * HALF; f32x4 x0, x1;
;                     if (xin32) { x0 = *(const f32x4*)(xin32 + o); x1 = *(const f32x4*)(xin32 + o + 4); }
;                     else { const u32x4 w = *(const u32x4*)(xb + o); x0 = (f32x4){bfl(w.x), bfh(w.x), bfl(w.y), bfh(w.y)}; x1 = (f32x4){bfl(w.z), bfh(w.z), bfl(w.w), bfh(w.w)}; }
;                     const f32x4 v0 = x0 + acc[ai][bj][m][0] * scale, v1 = x1 + acc[ai][bj][m][1] * scale;
;                     ss += ((v0[0] * v0[0] + v0[1] * v0[1]) + (v0[2] * v0[2] + v0[3] * v0[3])) + ((v1[0] * v1[0] + v1[1] * v1[1]) + (v1[2] * v1[2] + v1[3] * v1[3]));
;                     u32x4 w; w.x = cvt_pk_bf16(v0[0], v0[1]); w.y = cvt_pk_bf16(v0[2], v0[3]); w.z = cvt_pk_bf16(v1[0], v1[1]); w.w = cvt_pk_bf16(v1[2], v1[3]); st_wt16(xb + o, w); }
;                 ss += __shfl_xor(ss, 16); ss += __shfl_xor(ss, 32);
;                 if (fq == 0) P[(ai * HALF + wr * 64 + m * 16 + fr) * 4 + wc] = ss; }
.LBB0_379:
	s_or_b64 exec, exec, s[8:9]
	v_or_b32_e32 v80, 48, v128
	s_waitcnt lgkmcnt(0)
	v_ashrrev_i32_e32 v81, 31, v80
	v_lshlrev_b64 v[80:81], 10, v[80:81]
	v_lshl_add_u64 v[80:81], v[80:81], 0, v[130:131]
	v_lshl_add_u64 v[88:89], v[80:81], 1, s[54:55]
	v_lshlrev_b32_e32 v90, 16, v180
	v_and_b32_e32 v91, 0xffff0000, v180
	v_lshlrev_b32_e32 v80, 16, v181
	v_and_b32_e32 v81, 0xffff0000, v181
	v_lshlrev_b32_e32 v92, 16, v182
	v_and_b32_e32 v93, 0xffff0000, v182
	v_lshlrev_b32_e32 v82, 16, v183
	v_and_b32_e32 v83, 0xffff0000, v183
	v_lshlrev_b32_e32 v94, 16, v184
	v_and_b32_e32 v95, 0xffff0000, v184
	v_lshlrev_b32_e32 v84, 16, v185
	v_and_b32_e32 v85, 0xffff0000, v185
	v_lshlrev_b32_e32 v96, 16, v186
	v_and_b32_e32 v97, 0xffff0000, v186
	v_lshlrev_b32_e32 v86, 16, v187
	v_and_b32_e32 v87, 0xffff0000, v187
	v_pk_fma_f32 v[78:79], v[78:79], 0.5, v[80:81] op_sel_hi:[1,0,1]
	v_pk_fma_f32 v[76:77], v[76:77], 0.5, v[90:91] op_sel_hi:[1,0,1]
	v_pk_fma_f32 v[74:75], v[74:75], 0.5, v[82:83] op_sel_hi:[1,0,1]
	v_pk_fma_f32 v[72:73], v[72:73], 0.5, v[92:93] op_sel_hi:[1,0,1]
	v_pk_fma_f32 v[70:71], v[70:71], 0.5, v[84:85] op_sel_hi:[1,0,1]
	v_pk_fma_f32 v[68:69], v[68:69], 0.5, v[94:95] op_sel_hi:[1,0,1]
	v_pk_fma_f32 v[80:81], v[66:67], 0.5, v[86:87] op_sel_hi:[1,0,1]
	v_pk_fma_f32 v[82:83], v[64:65], 0.5, v[96:97] op_sel_hi:[1,0,1]
	v_mul_f32_e32 v66, v77, v77
	v_mul_f32_e32 v67, v79, v79
	v_mul_f32_e32 v84, v73, v73
	v_mul_f32_e32 v85, v75, v75
	v_cvt_pk_bf16_f32 v64, v76, v77
	v_cvt_pk_bf16_f32 v65, v78, v79
	v_mul_f32_e32 v77, v69, v69
	v_mul_f32_e32 v79, v71, v71
	v_mul_f32_e32 v86, v83, v83
	v_mul_f32_e32 v87, v81, v81
	v_fmac_f32_e32 v66, v76, v76
	v_fmac_f32_e32 v67, v78, v78
	v_fmac_f32_e32 v84, v72, v72
	v_fmac_f32_e32 v85, v74, v74
	v_fmac_f32_e32 v77, v68, v68
	v_fmac_f32_e32 v79, v70, v70
	v_fmac_f32_e32 v86, v82, v82
	v_fmac_f32_e32 v87, v80, v80
	v_add_f32_e32 v66, v66, v67
	v_add_f32_e32 v67, v84, v85
	v_add_f32_e32 v76, v77, v79
	v_add_f32_e32 v77, v86, v87
	v_add_f32_e32 v66, v66, v67
	v_add_f32_e32 v67, v76, v77
	v_add_f32_e32 v76, v66, v67
	ds_bpermute_b32 v77, v133, v76
	v_cvt_pk_bf16_f32 v66, v72, v73
	v_cvt_pk_bf16_f32 v67, v74, v75
	global_store_dwordx4 v[88:89], v[64:67], off
	s_waitcnt lgkmcnt(0)
	s_nop 0
	v_add_f32_e32 v64, v76, v77
	ds_bpermute_b32 v65, v132, v64
	v_cvt_pk_bf16_f32 v66, v68, v69
	v_cvt_pk_bf16_f32 v67, v70, v71
	v_cvt_pk_bf16_f32 v68, v82, v83
	v_cvt_pk_bf16_f32 v69, v80, v81
	global_store_dwordx4 v[88:89], v[66:69], off offset:256
	s_and_saveexec_b64 s[8:9], s[4:5]
	s_cbranch_execz .LBB0_381
	s_waitcnt lgkmcnt(0)
	v_add_f32_e32 v64, v64, v65
	ds_write_b32 v112, v64 offset:768
.LBB0_381:
	s_or_b64 exec, exec, s[8:9]
	s_waitcnt lgkmcnt(0)
	v_lshlrev_b64 v[64:65], 10, v[128:129]
	v_lshl_add_u64 v[64:65], v[64:65], 0, v[130:131]
	v_lshl_add_u64 v[64:65], v[64:65], 1, s[54:55]
	v_add_co_u32_e32 v74, vcc, 0x40000, v64
	s_mov_b64 s[8:9], 0x40000
	s_nop 0
	v_addc_co_u32_e32 v75, vcc, 0, v65, vcc
	v_lshl_add_u64 v[76:77], v[64:65], 0, s[8:9]
	v_lshlrev_b32_e32 v78, 16, v188
	v_and_b32_e32 v79, 0xffff0000, v188
	v_lshlrev_b32_e32 v66, 16, v189
	v_and_b32_e32 v67, 0xffff0000, v189
	v_lshlrev_b32_e32 v80, 16, v190
	v_and_b32_e32 v81, 0xffff0000, v190
	v_lshlrev_b32_e32 v68, 16, v191
	v_and_b32_e32 v69, 0xffff0000, v191
	v_lshlrev_b32_e32 v82, 16, v192
	v_and_b32_e32 v83, 0xffff0000, v192
	v_lshlrev_b32_e32 v70, 16, v193
	v_and_b32_e32 v71, 0xffff0000, v193
	v_lshlrev_b32_e32 v84, 16, v194
	v_and_b32_e32 v85, 0xffff0000, v194
	v_lshlrev_b32_e32 v72, 16, v195
	v_and_b32_e32 v73, 0xffff0000, v195
	v_pk_fma_f32 v[62:63], v[62:63], 0.5, v[66:67] op_sel_hi:[1,0,1]
	v_pk_fma_f32 v[60:61], v[60:61], 0.5, v[78:79] op_sel_hi:[1,0,1]
	v_pk_fma_f32 v[58:59], v[58:59], 0.5, v[68:69] op_sel_hi:[1,0,1]
	v_pk_fma_f32 v[56:57], v[56:57], 0.5, v[80:81] op_sel_hi:[1,0,1]
	v_pk_fma_f32 v[54:55], v[54:55], 0.5, v[70:71] op_sel_hi:[1,0,1]
	v_pk_fma_f32 v[52:53], v[52:53], 0.5, v[82:83] op_sel_hi:[1,0,1]
	v_pk_fma_f32 v[66:67], v[50:51], 0.5, v[72:73] op_sel_hi:[1,0,1]
	v_pk_fma_f32 v[68:69], v[48:49], 0.5, v[84:85] op_sel_hi:[1,0,1]
	v_mul_f32_e32 v50, v61, v61
	v_mul_f32_e32 v51, v63, v63
	v_mul_f32_e32 v70, v57, v57
	v_mul_f32_e32 v71, v59, v59
	v_cvt_pk_bf16_f32 v48, v60, v61
	v_cvt_pk_bf16_f32 v49, v62, v63
	v_mul_f32_e32 v61, v53, v53
	v_mul_f32_e32 v63, v55, v55
	v_mul_f32_e32 v72, v69, v69
	v_mul_f32_e32 v73, v67, v67
	v_fmac_f32_e32 v50, v60, v60
	v_fmac_f32_e32 v51, v62, v62
	v_fmac_f32_e32 v70, v56, v56
	v_fmac_f32_e32 v71, v58, v58
	v_fmac_f32_e32 v61, v52, v52
	v_fmac_f32_e32 v63, v54, v54
	v_fmac_f32_e32 v72, v68, v68
	v_fmac_f32_e32 v73, v66, v66
	v_add_f32_e32 v50, v50, v51
	v_add_f32_e32 v51, v70, v71
	v_add_f32_e32 v60, v61, v63
	v_add_f32_e32 v61, v72, v73
	v_add_f32_e32 v50, v50, v51
	v_add_f32_e32 v51, v60, v61
	v_add_f32_e32 v60, v50, v51
	ds_bpermute_b32 v61, v133, v60
	v_cvt_pk_bf16_f32 v50, v56, v57
	v_cvt_pk_bf16_f32 v51, v58, v59
	global_store_dwordx4 v[74:75], v[48:51], off
	s_waitcnt lgkmcnt(0)
	s_nop 0
	v_add_f32_e32 v48, v60, v61
	ds_bpermute_b32 v49, v132, v48
	v_cvt_pk_bf16_f32 v50, v52, v53
	v_cvt_pk_bf16_f32 v51, v54, v55
	v_cvt_pk_bf16_f32 v52, v68, v69
	v_cvt_pk_bf16_f32 v53, v66, v67
	global_store_dwordx4 v[76:77], v[50:53], off offset:256
	s_and_saveexec_b64 s[8:9], s[4:5]
	s_cbranch_execz .LBB0_383
	s_waitcnt lgkmcnt(0)
	v_add_f32_e32 v48, v48, v49
	ds_write_b32 v112, v48 offset:2048
; __device__ __forceinline__ unsigned cvt_pk_bf16(float lo, float hi) { cvf32x2_t v = {lo, hi}; cvbf16x2_t b = __builtin_convertvector(v, cvbf16x2_t); return __builtin_bit_cast(unsigned, b); }
; __device__ __forceinline__ float bfl(unsigned w) { return __uint_as_float(w << 16); }
; __device__ __forceinline__ float bfh(unsigned w) { return __uint_as_float(w & 0xffff0000u); }
;     __device__ __forceinline__ void fused(f32x4 (&acc)[2][2][4][2], const Unit& u, int wr, int wc, int fr, int fq, PG8_LAS unsigned char* lds, int wid, int lane) const {
;     ...
;             for (int m = 0; m < 4; ++m) { const int row = row0 + ai * HALF + m * 16; const size_t off = (size_t)row * 1024 + col0; float ss = 0.f;
; #pragma unroll
;                 for (int bj = 0; bj < 2; ++bj) { const size_t o = off + bj * HALF; f32x4 x0, x1;
;                     if (xin32) { x0 = *(const f32x4*)(xin32 + o); x1 = *(const f32x4*)(xin32 + o + 4); }
;                     else { const u32x4 w = *(const u32x4*)(xb + o); x0 = (f32x4){bfl(w.x), bfh(w.x), bfl(w.y), bfh(w.y)}; x1 = (f32x4){bfl(w.z), bfh(w.z), bfl(w.w), bfh(w.w)}; }
;                     const f32x4 v0 = x0 + acc[ai][bj][m][0] * scale, v1 = x1 + acc[ai][bj][m][1] * scale;
;                     ss += ((v0[0] * v0[0] + v0[1] * v0[1]) + (v0[2] * v0[2] + v0[3] * v0[3])) + ((v1[0] * v1[0] + v1[1] * v1[1]) + (v1[2] * v1[2] + v1[3] * v1[3]));
;                     u32x4 w; w.x = cvt_pk_bf16(v0[0], v0[1]); w.y = cvt_pk_bf16(v0[2], v0[3]); w.z = cvt_pk_bf16(v1[0], v1[1]); w.w = cvt_pk_bf16(v1[2], v1[3]); st_wt16(xb + o, w); }
;                 ss += __shfl_xor(ss, 16); ss += __shfl_xor(ss, 32);
;                 if (fq == 0) P[(ai * HALF + wr * 64 + m * 16 + fr) * 4 + wc] = ss; }
.LBB0_383:
	s_or_b64 exec, exec, s[8:9]
	v_add_co_u32_e32 v56, vcc, 0x48000, v64
	s_mov_b64 s[8:9], 0x48000
	s_nop 0
	v_addc_co_u32_e32 v57, vcc, 0, v65, vcc
	v_lshl_add_u64 v[58:59], v[64:65], 0, s[8:9]
	s_waitcnt lgkmcnt(0)
	v_lshlrev_b32_e32 v60, 16, v196
	v_and_b32_e32 v61, 0xffff0000, v196
	v_lshlrev_b32_e32 v48, 16, v197
	v_and_b32_e32 v49, 0xffff0000, v197
	v_lshlrev_b32_e32 v62, 16, v198
	v_and_b32_e32 v63, 0xffff0000, v198
	v_lshlrev_b32_e32 v50, 16, v199
	v_and_b32_e32 v51, 0xffff0000, v199
	v_lshlrev_b32_e32 v64, 16, v200
	v_and_b32_e32 v65, 0xffff0000, v200
	v_lshlrev_b32_e32 v52, 16, v201
	v_and_b32_e32 v53, 0xffff0000, v201
	v_lshlrev_b32_e32 v66, 16, v202
	v_and_b32_e32 v67, 0xffff0000, v202
	v_lshlrev_b32_e32 v54, 16, v203
	v_and_b32_e32 v55, 0xffff0000, v203
	v_pk_fma_f32 v[46:47], v[46:47], 0.5, v[48:49] op_sel_hi:[1,0,1]
	v_pk_fma_f32 v[44:45], v[44:45], 0.5, v[60:61] op_sel_hi:[1,0,1]
	v_pk_fma_f32 v[42:43], v[42:43], 0.5, v[50:51] op_sel_hi:[1,0,1]
	v_pk_fma_f32 v[40:41], v[40:41], 0.5, v[62:63] op_sel_hi:[1,0,1]
	v_pk_fma_f32 v[38:39], v[38:39], 0.5, v[52:53] op_sel_hi:[1,0,1]
	v_pk_fma_f32 v[36:37], v[36:37], 0.5, v[64:65] op_sel_hi:[1,0,1]
	v_pk_fma_f32 v[48:49], v[34:35], 0.5, v[54:55] op_sel_hi:[1,0,1]
	v_pk_fma_f32 v[50:51], v[32:33], 0.5, v[66:67] op_sel_hi:[1,0,1]
	v_mul_f32_e32 v34, v45, v45
	v_mul_f32_e32 v35, v47, v47
	v_mul_f32_e32 v52, v41, v41
	v_mul_f32_e32 v53, v43, v43
	v_cvt_pk_bf16_f32 v32, v44, v45
	v_cvt_pk_bf16_f32 v33, v46, v47
	v_mul_f32_e32 v45, v37, v37
	v_mul_f32_e32 v47, v39, v39
	v_mul_f32_e32 v54, v51, v51
	v_mul_f32_e32 v55, v49, v49
	v_fmac_f32_e32 v34, v44, v44
	v_fmac_f32_e32 v35, v46, v46
	v_fmac_f32_e32 v52, v40, v40
	v_fmac_f32_e32 v53, v42, v42
	v_fmac_f32_e32 v45, v36, v36
	v_fmac_f32_e32 v47, v38, v38
	v_fmac_f32_e32 v54, v50, v50
	v_fmac_f32_e32 v55, v48, v48
	v_add_f32_e32 v34, v34, v35
	v_add_f32_e32 v35, v52, v53
	v_add_f32_e32 v44, v45, v47
	v_add_f32_e32 v45, v54, v55
	v_add_f32_e32 v34, v34, v35
	v_add_f32_e32 v35, v44, v45
	v_add_f32_e32 v44, v34, v35
	ds_bpermute_b32 v45, v133, v44
	v_cvt_pk_bf16_f32 v34, v40, v41
	v_cvt_pk_bf16_f32 v35, v42, v43
	global_store_dwordx4 v[56:57], v[32:35], off
	s_waitcnt lgkmcnt(0)
	s_nop 0
	v_add_f32_e32 v32, v44, v45
	ds_bpermute_b32 v33, v132, v32
	v_cvt_pk_bf16_f32 v34, v36, v37
	v_cvt_pk_bf16_f32 v35, v38, v39
	v_cvt_pk_bf16_f32 v36, v50, v51
	v_cvt_pk_bf16_f32 v37, v48, v49
	global_store_dwordx4 v[58:59], v[34:37], off offset:256
	s_and_saveexec_b64 s[8:9], s[4:5]
	s_cbranch_execz .LBB0_385
	s_waitcnt lgkmcnt(0)
	v_add_f32_e32 v32, v32, v33
	ds_write_b32 v112, v32 offset:2304
; __device__ __forceinline__ unsigned cvt_pk_bf16(float lo, float hi) { cvf32x2_t v = {lo, hi}; cvbf16x2_t b = __builtin_convertvector(v, cvbf16x2_t); return __builtin_bit_cast(unsigned, b); }
; __device__ __forceinline__ float bfl(unsigned w) { return __uint_as_float(w << 16); }
; __device__ __forceinline__ float bfh(unsigned w) { return __uint_as_float(w & 0xffff0000u); }
;     __device__ __forceinline__ void fused(f32x4 (&acc)[2][2][4][2], const Unit& u, int wr, int wc, int fr, int fq, PG8_LAS unsigned char* lds, int wid, int lane) const {
;     ...
;             for (int m = 0; m < 4; ++m) { const int row = row0 + ai * HALF + m * 16; const size_t off = (size_t)row * 1024 + col0; float ss = 0.f;
; #pragma unroll
;                 for (int bj = 0; bj < 2; ++bj) { const size_t o = off + bj * HALF; f32x4 x0, x1;
;                     if (xin32) { x0 = *(const f32x4*)(xin32 + o); x1 = *(const f32x4*)(xin32 + o + 4); }
;                     else { const u32x4 w = *(const u32x4*)(xb + o); x0 = (f32x4){bfl(w.x), bfh(w.x), bfl(w.y), bfh(w.y)}; x1 = (f32x4){bfl(w.z), bfh(w.z), bfl(w.w), bfh(w.w)}; }
;                     const f32x4 v0 = x0 + acc[ai][bj][m][0] * scale, v1 = x1 + acc[ai][bj][m][1] * scale;
;                     ss += ((v0[0] * v0[0] + v0[1] * v0[1]) + (v0[2] * v0[2] + v0[3] * v0[3])) + ((v1[0] * v1[0] + v1[1] * v1[1]) + (v1[2] * v1[2] + v1[3] * v1[3]));
;                     u32x4 w; w.x = cvt_pk_bf16(v0[0], v0[1]); w.y = cvt_pk_bf16(v0[2], v0[3]); w.z = cvt_pk_bf16(v1[0], v1[1]); w.w = cvt_pk_bf16(v1[2], v1[3]); st_wt16(xb + o, w); }
;                 ss += __shfl_xor(ss, 16); ss += __shfl_xor(ss, 32);
;                 if (fq == 0) P[(ai * HALF + wr * 64 + m * 16 + fr) * 4 + wc] = ss; }
.LBB0_385:
	s_or_b64 exec, exec, s[8:9]
	s_waitcnt lgkmcnt(0)
	v_lshlrev_b64 v[32:33], 10, v[128:129]
	v_lshl_add_u64 v[32:33], v[32:33], 0, v[130:131]
	v_lshl_add_u64 v[32:33], v[32:33], 1, s[54:55]
	v_add_co_u32_e32 v42, vcc, 0x50000, v32
	s_mov_b64 s[8:9], 0x50000
	s_nop 0
	v_addc_co_u32_e32 v43, vcc, 0, v33, vcc
	v_lshl_add_u64 v[44:45], v[32:33], 0, s[8:9]
	v_lshlrev_b32_e32 v46, 16, v204
	v_and_b32_e32 v47, 0xffff0000, v204
	v_lshlrev_b32_e32 v34, 16, v205
	v_and_b32_e32 v35, 0xffff0000, v205
	v_lshlrev_b32_e32 v48, 16, v206
	v_and_b32_e32 v49, 0xffff0000, v206
	v_lshlrev_b32_e32 v36, 16, v207
	v_and_b32_e32 v37, 0xffff0000, v207
	v_lshlrev_b32_e32 v50, 16, v212
	v_and_b32_e32 v51, 0xffff0000, v212
	v_lshlrev_b32_e32 v38, 16, v213
	v_and_b32_e32 v39, 0xffff0000, v213
	v_lshlrev_b32_e32 v52, 16, v214
	v_and_b32_e32 v53, 0xffff0000, v214
	v_lshlrev_b32_e32 v40, 16, v215
	v_and_b32_e32 v41, 0xffff0000, v215
	v_pk_fma_f32 v[30:31], v[30:31], 0.5, v[34:35] op_sel_hi:[1,0,1]
	v_pk_fma_f32 v[28:29], v[28:29], 0.5, v[46:47] op_sel_hi:[1,0,1]
	v_pk_fma_f32 v[26:27], v[26:27], 0.5, v[36:37] op_sel_hi:[1,0,1]
	v_pk_fma_f32 v[24:25], v[24:25], 0.5, v[48:49] op_sel_hi:[1,0,1]
	v_pk_fma_f32 v[22:23], v[22:23], 0.5, v[38:39] op_sel_hi:[1,0,1]
	v_pk_fma_f32 v[20:21], v[20:21], 0.5, v[50:51] op_sel_hi:[1,0,1]
	v_pk_fma_f32 v[34:35], v[18:19], 0.5, v[40:41] op_sel_hi:[1,0,1]
	v_pk_fma_f32 v[36:37], v[16:17], 0.5, v[52:53] op_sel_hi:[1,0,1]
	v_mul_f32_e32 v18, v29, v29
	v_mul_f32_e32 v19, v31, v31
	v_mul_f32_e32 v38, v25, v25
	v_mul_f32_e32 v39, v27, v27
	v_cvt_pk_bf16_f32 v16, v28, v29
	v_cvt_pk_bf16_f32 v17, v30, v31
	v_mul_f32_e32 v29, v21, v21
	v_mul_f32_e32 v31, v23, v23
	v_mul_f32_e32 v40, v37, v37
	v_mul_f32_e32 v41, v35, v35
	v_fmac_f32_e32 v18, v28, v28
	v_fmac_f32_e32 v19, v30, v30
	v_fmac_f32_e32 v38, v24, v24
	v_fmac_f32_e32 v39, v26, v26
	v_fmac_f32_e32 v29, v20, v20
	v_fmac_f32_e32 v31, v22, v22
	v_fmac_f32_e32 v40, v36, v36
	v_fmac_f32_e32 v41, v34, v34
	v_add_f32_e32 v18, v18, v19
	v_add_f32_e32 v19, v38, v39
	v_add_f32_e32 v28, v29, v31
	v_add_f32_e32 v29, v40, v41
	v_add_f32_e32 v18, v18, v19
	v_add_f32_e32 v19, v28, v29
	v_add_f32_e32 v28, v18, v19
	ds_bpermute_b32 v29, v133, v28
	v_cvt_pk_bf16_f32 v18, v24, v25
	v_cvt_pk_bf16_f32 v19, v26, v27
	global_store_dwordx4 v[42:43], v[16:19], off
	s_waitcnt lgkmcnt(0)
	s_nop 0
	v_add_f32_e32 v16, v28, v29
	ds_bpermute_b32 v17, v132, v16
	v_cvt_pk_bf16_f32 v18, v20, v21
	v_cvt_pk_bf16_f32 v19, v22, v23
	v_cvt_pk_bf16_f32 v20, v36, v37
	v_cvt_pk_bf16_f32 v21, v34, v35
	global_store_dwordx4 v[44:45], v[18:21], off offset:256
	s_and_saveexec_b64 s[8:9], s[4:5]
	s_cbranch_execz .LBB0_387
	s_waitcnt lgkmcnt(0)
	v_add_f32_e32 v16, v16, v17
	ds_write_b32 v112, v16 offset:2560
.LBB0_387:
	s_or_b64 exec, exec, s[8:9]
	v_add_co_u32_e32 v24, vcc, 0x58000, v32
	s_mov_b64 s[8:9], 0x58000
	s_nop 0
	v_addc_co_u32_e32 v25, vcc, 0, v33, vcc
	v_lshl_add_u64 v[26:27], v[32:33], 0, s[8:9]
	s_waitcnt lgkmcnt(0)
	v_lshlrev_b32_e32 v28, 16, v216
	v_and_b32_e32 v29, 0xffff0000, v216
	v_lshlrev_b32_e32 v16, 16, v217
	v_and_b32_e32 v17, 0xffff0000, v217
	v_lshlrev_b32_e32 v30, 16, v218
	v_and_b32_e32 v31, 0xffff0000, v218
	v_lshlrev_b32_e32 v18, 16, v219
	v_and_b32_e32 v19, 0xffff0000, v219
	v_lshlrev_b32_e32 v32, 16, v220
	v_and_b32_e32 v33, 0xffff0000, v220
	v_lshlrev_b32_e32 v20, 16, v221
	v_and_b32_e32 v21, 0xffff0000, v221
	v_lshlrev_b32_e32 v34, 16, v222
	v_and_b32_e32 v35, 0xffff0000, v222
	v_lshlrev_b32_e32 v22, 16, v223
	v_and_b32_e32 v23, 0xffff0000, v223
	v_pk_fma_f32 v[14:15], v[14:15], 0.5, v[16:17] op_sel_hi:[1,0,1]
	v_pk_fma_f32 v[12:13], v[12:13], 0.5, v[28:29] op_sel_hi:[1,0,1]
	v_pk_fma_f32 v[10:11], v[10:11], 0.5, v[18:19] op_sel_hi:[1,0,1]
	v_pk_fma_f32 v[8:9], v[8:9], 0.5, v[30:31] op_sel_hi:[1,0,1]
	v_pk_fma_f32 v[6:7], v[6:7], 0.5, v[20:21] op_sel_hi:[1,0,1]
	v_pk_fma_f32 v[4:5], v[4:5], 0.5, v[32:33] op_sel_hi:[1,0,1]
	v_pk_fma_f32 v[16:17], v[2:3], 0.5, v[22:23] op_sel_hi:[1,0,1]
	v_pk_fma_f32 v[18:19], v[0:1], 0.5, v[34:35] op_sel_hi:[1,0,1]
	v_mul_f32_e32 v2, v13, v13
	v_mul_f32_e32 v3, v15, v15
	v_mul_f32_e32 v20, v9, v9
	v_mul_f32_e32 v21, v11, v11
	v_cvt_pk_bf16_f32 v0, v12, v13
	v_cvt_pk_bf16_f32 v1, v14, v15
	v_mul_f32_e32 v13, v5, v5
	v_mul_f32_e32 v15, v7, v7
	v_mul_f32_e32 v22, v19, v19
	v_mul_f32_e32 v23, v17, v17
	v_fmac_f32_e32 v2, v12, v12
	v_fmac_f32_e32 v3, v14, v14
	v_fmac_f32_e32 v20, v8, v8
	v_fmac_f32_e32 v21, v10, v10
	v_fmac_f32_e32 v13, v4, v4
	v_fmac_f32_e32 v15, v6, v6
	v_fmac_f32_e32 v22, v18, v18
	v_fmac_f32_e32 v23, v16, v16
	v_add_f32_e32 v2, v2, v3
	v_add_f32_e32 v3, v20, v21
	v_add_f32_e32 v12, v13, v15
	v_add_f32_e32 v13, v22, v23
	v_add_f32_e32 v2, v2, v3
	v_add_f32_e32 v3, v12, v13
	v_add_f32_e32 v12, v2, v3
	ds_bpermute_b32 v13, v133, v12
	v_cvt_pk_bf16_f32 v2, v8, v9
	v_cvt_pk_bf16_f32 v3, v10, v11
	global_store_dwordx4 v[24:25], v[0:3], off
	s_waitcnt lgkmcnt(0)
	s_nop 0
	v_add_f32_e32 v0, v12, v13
	ds_bpermute_b32 v1, v132, v0
	v_cvt_pk_bf16_f32 v2, v4, v5
	v_cvt_pk_bf16_f32 v3, v6, v7
	v_cvt_pk_bf16_f32 v4, v18, v19
	v_cvt_pk_bf16_f32 v5, v16, v17
	global_store_dwordx4 v[26:27], v[2:5], off offset:256
	s_and_saveexec_b64 s[8:9], s[4:5]
	s_cbranch_execz .LBB0_389
	s_waitcnt lgkmcnt(0)
	v_add_f32_e32 v0, v0, v1
	ds_write_b32 v112, v0 offset:2816
